# P6': the polling wave fetches the panel's 256 row statistics once and shares them through LDS (instead of 8 sc1 loads in every wave); rest as v058
# speedup vs baseline: 1.0064x; 1.0014x over previous
.Lp6_fetch:
	v_and_b32_e32 v181, 0xfffffc00, v253
	v_lshl_add_u32 v181, v186, 2, v181
	global_load_dword v188, v181, s[16:17] offset:0 sc1
	global_load_dword v189, v181, s[16:17] offset:256 sc1
	global_load_dword v190, v181, s[16:17] offset:512 sc1
	global_load_dword v191, v181, s[16:17] offset:768 sc1
	v_lshlrev_b32_e32 v181, 2, v186
	v_add_u32_e32 v181, 0x21800, v181
	s_waitcnt vmcnt(0)
	ds_write_b32 v181, v188 offset:0
	ds_write_b32 v181, v189 offset:256
	ds_write_b32 v181, v190 offset:512
	ds_write_b32 v181, v191 offset:768
	s_waitcnt lgkmcnt(0)

.Lp6_part2:
	v_and_b32_e32 v181, 0x3ff, v253
	v_add_u32_e32 v181, 0x21800, v181
	ds_read_b32 v164, v181
	ds_read_b32 v165, v181 offset:64
	ds_read_b32 v166, v181 offset:128
	ds_read_b32 v167, v181 offset:192
	ds_read_b32 v168, v181 offset:512
	ds_read_b32 v169, v181 offset:576
	ds_read_b32 v170, v181 offset:640
	ds_read_b32 v171, v181 offset:704
	s_waitcnt lgkmcnt(0)
	v_fmamk_f32 v128, v164, 0x3a000000, v177
	v_mul_f32_e32 v129, 0x4f800000, v128
	v_cmp_gt_f32_e32 vcc, s9, v128
	s_nop 1
	v_cndmask_b32_e32 v128, v128, v129, vcc
	v_sqrt_f32_e32 v129, v128
	s_nop 0
	v_add_u32_e32 v130, -1, v129
	v_add_u32_e32 v131, 1, v129
	v_fma_f32 v132, -v130, v129, v128
	v_fma_f32 v133, -v131, v129, v128
	v_cmp_ge_f32_e64 s[2:3], 0, v132
	s_nop 1
	v_cndmask_b32_e64 v129, v129, v130, s[2:3]
	v_cmp_lt_f32_e64 s[2:3], 0, v133
	s_nop 1
	v_cndmask_b32_e64 v129, v129, v131, s[2:3]
	v_mul_f32_e32 v130, 0x37800000, v129
	v_cndmask_b32_e32 v129, v129, v130, vcc
	v_cmp_class_f32_e32 vcc, v128, v178
	s_nop 1
	v_cndmask_b32_e32 v128, v129, v128, vcc
	v_div_scale_f32 v129, s[2:3], v128, v128, 1.0
	v_rcp_f32_e32 v130, v129
	v_div_scale_f32 v131, vcc, 1.0, v128, 1.0
	v_fma_f32 v132, -v129, v130, 1.0
	v_fmac_f32_e32 v130, v132, v130
	v_mul_f32_e32 v132, v131, v130
	v_fma_f32 v133, -v129, v132, v131
	v_fmac_f32_e32 v132, v133, v130
	v_fma_f32 v129, -v129, v132, v131
	v_div_fmas_f32 v129, v129, v130, v132
	v_div_fixup_f32 v184, v129, v128, 1.0
	s_mov_b32 s100, s64
	s_mov_b32 s101, s65
	v_mov_b32_e32 v244, v185
	v_mov_b32_e32 v245, 0
	v_lshl_add_u64 v[246:247], s[100:101], 0, v[244:245]
	v_pk_mul_f32 v[188:189], v[124:125], v[184:185] op_sel_hi:[1,0]
	v_pk_mul_f32 v[190:191], v[126:127], v[184:185] op_sel_hi:[1,0]
	v_pk_mul_f32 v[192:193], v[120:121], v[184:185] op_sel_hi:[1,0]
	v_pk_mul_f32 v[194:195], v[122:123], v[184:185] op_sel_hi:[1,0]
	v_pk_mul_f32 v[188:189], v[148:149], v[188:189]
	v_pk_mul_f32 v[190:191], v[150:151], v[190:191]
	v_pk_mul_f32 v[192:193], v[152:153], v[192:193]
	v_pk_mul_f32 v[194:195], v[154:155], v[194:195]
	s_nop 1
	v_permlane16_swap_b32_e32 v188, v192
	v_permlane16_swap_b32_e32 v189, v193
	v_permlane16_swap_b32_e32 v190, v194
	v_permlane16_swap_b32_e32 v191, v195
	v_permlane32_swap_b32_e32 v188, v192
	v_permlane32_swap_b32_e32 v189, v193
	v_permlane32_swap_b32_e32 v190, v194
	v_permlane32_swap_b32_e32 v191, v195
	s_nop 1
	global_store_dwordx4 v[246:247], v[188:191], off offset:0
	global_store_dwordx4 v[246:247], v[192:195], off offset:64
	v_pk_mul_f32 v[196:197], v[116:117], v[184:185] op_sel_hi:[1,0]
	v_pk_mul_f32 v[198:199], v[118:119], v[184:185] op_sel_hi:[1,0]
	v_pk_mul_f32 v[200:201], v[112:113], v[184:185] op_sel_hi:[1,0]
	v_pk_mul_f32 v[202:203], v[114:115], v[184:185] op_sel_hi:[1,0]
	v_pk_mul_f32 v[196:197], v[156:157], v[196:197]
	v_pk_mul_f32 v[198:199], v[158:159], v[198:199]
	v_pk_mul_f32 v[200:201], v[160:161], v[200:201]
	v_pk_mul_f32 v[202:203], v[162:163], v[202:203]
	s_nop 1
	v_permlane16_swap_b32_e32 v196, v200
	v_permlane16_swap_b32_e32 v197, v201
	v_permlane16_swap_b32_e32 v198, v202
	v_permlane16_swap_b32_e32 v199, v203
	v_permlane32_swap_b32_e32 v196, v200
	v_permlane32_swap_b32_e32 v197, v201
	v_permlane32_swap_b32_e32 v198, v202
	v_permlane32_swap_b32_e32 v199, v203
	s_nop 1
	global_store_dwordx4 v[246:247], v[196:199], off offset:512
	global_store_dwordx4 v[246:247], v[200:203], off offset:576
	v_fmamk_f32 v128, v165, 0x3a000000, v177
	v_mul_f32_e32 v129, 0x4f800000, v128
	v_cmp_gt_f32_e32 vcc, s9, v128
	s_nop 1
	v_cndmask_b32_e32 v128, v128, v129, vcc
	v_sqrt_f32_e32 v129, v128
	s_nop 0
	v_add_u32_e32 v130, -1, v129
	v_add_u32_e32 v131, 1, v129
	v_fma_f32 v132, -v130, v129, v128
	v_fma_f32 v133, -v131, v129, v128
	v_cmp_ge_f32_e64 s[2:3], 0, v132
	s_nop 1
	v_cndmask_b32_e64 v129, v129, v130, s[2:3]
	v_cmp_lt_f32_e64 s[2:3], 0, v133
	s_nop 1
	v_cndmask_b32_e64 v129, v129, v131, s[2:3]
	v_mul_f32_e32 v130, 0x37800000, v129
	v_cndmask_b32_e32 v129, v129, v130, vcc
	v_cmp_class_f32_e32 vcc, v128, v178
	s_nop 1
	v_cndmask_b32_e32 v128, v129, v128, vcc
	v_div_scale_f32 v129, s[2:3], v128, v128, 1.0
	v_rcp_f32_e32 v130, v129
	v_div_scale_f32 v131, vcc, 1.0, v128, 1.0
	v_fma_f32 v132, -v129, v130, 1.0
	v_fmac_f32_e32 v130, v132, v130
	v_mul_f32_e32 v132, v131, v130
	v_fma_f32 v133, -v129, v132, v131
	v_fmac_f32_e32 v132, v133, v130
	v_fma_f32 v129, -v129, v132, v131
	v_div_fmas_f32 v129, v129, v130, v132
	v_div_fixup_f32 v184, v129, v128, 1.0
	s_add_u32 s100, s64, 0x20000
	s_addc_u32 s101, s65, 0
	v_lshl_add_u64 v[248:249], s[100:101], 0, v[244:245]
	v_pk_mul_f32 v[204:205], v[108:109], v[184:185] op_sel_hi:[1,0]
	v_pk_mul_f32 v[206:207], v[110:111], v[184:185] op_sel_hi:[1,0]
	v_pk_mul_f32 v[208:209], v[104:105], v[184:185] op_sel_hi:[1,0]
	v_pk_mul_f32 v[210:211], v[106:107], v[184:185] op_sel_hi:[1,0]
	v_pk_mul_f32 v[204:205], v[148:149], v[204:205]
	v_pk_mul_f32 v[206:207], v[150:151], v[206:207]
	v_pk_mul_f32 v[208:209], v[152:153], v[208:209]
	v_pk_mul_f32 v[210:211], v[154:155], v[210:211]
	s_nop 1
	v_permlane16_swap_b32_e32 v204, v208
	v_permlane16_swap_b32_e32 v205, v209
	v_permlane16_swap_b32_e32 v206, v210
	v_permlane16_swap_b32_e32 v207, v211
	v_permlane32_swap_b32_e32 v204, v208
	v_permlane32_swap_b32_e32 v205, v209
	v_permlane32_swap_b32_e32 v206, v210
	v_permlane32_swap_b32_e32 v207, v211
	s_nop 1
	global_store_dwordx4 v[248:249], v[204:207], off offset:0
	global_store_dwordx4 v[248:249], v[208:211], off offset:64
	v_pk_mul_f32 v[212:213], v[100:101], v[184:185] op_sel_hi:[1,0]
	v_pk_mul_f32 v[214:215], v[102:103], v[184:185] op_sel_hi:[1,0]
	v_pk_mul_f32 v[216:217], v[96:97], v[184:185] op_sel_hi:[1,0]
	v_pk_mul_f32 v[218:219], v[98:99], v[184:185] op_sel_hi:[1,0]
	v_pk_mul_f32 v[212:213], v[156:157], v[212:213]
	v_pk_mul_f32 v[214:215], v[158:159], v[214:215]
	v_pk_mul_f32 v[216:217], v[160:161], v[216:217]
	v_pk_mul_f32 v[218:219], v[162:163], v[218:219]
	s_nop 1
	v_permlane16_swap_b32_e32 v212, v216
	v_permlane16_swap_b32_e32 v213, v217
	v_permlane16_swap_b32_e32 v214, v218
	v_permlane16_swap_b32_e32 v215, v219
	v_permlane32_swap_b32_e32 v212, v216
	v_permlane32_swap_b32_e32 v213, v217
	v_permlane32_swap_b32_e32 v214, v218
	v_permlane32_swap_b32_e32 v215, v219
	s_nop 1
	global_store_dwordx4 v[248:249], v[212:215], off offset:512
	global_store_dwordx4 v[248:249], v[216:219], off offset:576
	v_fmamk_f32 v128, v166, 0x3a000000, v177
	v_mul_f32_e32 v129, 0x4f800000, v128
	v_cmp_gt_f32_e32 vcc, s9, v128
	s_nop 1
	v_cndmask_b32_e32 v128, v128, v129, vcc
	v_sqrt_f32_e32 v129, v128
	s_nop 0
	v_add_u32_e32 v130, -1, v129
	v_add_u32_e32 v131, 1, v129
	v_fma_f32 v132, -v130, v129, v128
	v_fma_f32 v133, -v131, v129, v128
	v_cmp_ge_f32_e64 s[2:3], 0, v132
	s_nop 1
	v_cndmask_b32_e64 v129, v129, v130, s[2:3]
	v_cmp_lt_f32_e64 s[2:3], 0, v133
	s_nop 1
	v_cndmask_b32_e64 v129, v129, v131, s[2:3]
	v_mul_f32_e32 v130, 0x37800000, v129
	v_cndmask_b32_e32 v129, v129, v130, vcc
	v_cmp_class_f32_e32 vcc, v128, v178
	s_nop 1
	v_cndmask_b32_e32 v128, v129, v128, vcc
	v_div_scale_f32 v129, s[2:3], v128, v128, 1.0
	v_rcp_f32_e32 v130, v129
	v_div_scale_f32 v131, vcc, 1.0, v128, 1.0
	v_fma_f32 v132, -v129, v130, 1.0
	v_fmac_f32_e32 v130, v132, v130
	v_mul_f32_e32 v132, v131, v130
	v_fma_f32 v133, -v129, v132, v131
	v_fmac_f32_e32 v132, v133, v130
	v_fma_f32 v129, -v129, v132, v131
	v_div_fmas_f32 v129, v129, v130, v132
	v_div_fixup_f32 v184, v129, v128, 1.0
	s_add_u32 s100, s64, 0x40000
	s_addc_u32 s101, s65, 0
	v_lshl_add_u64 v[246:247], s[100:101], 0, v[244:245]
	v_pk_mul_f32 v[220:221], v[92:93], v[184:185] op_sel_hi:[1,0]
	v_pk_mul_f32 v[222:223], v[94:95], v[184:185] op_sel_hi:[1,0]
	v_pk_mul_f32 v[224:225], v[88:89], v[184:185] op_sel_hi:[1,0]
	v_pk_mul_f32 v[226:227], v[90:91], v[184:185] op_sel_hi:[1,0]
	v_pk_mul_f32 v[220:221], v[148:149], v[220:221]
	v_pk_mul_f32 v[222:223], v[150:151], v[222:223]
	v_pk_mul_f32 v[224:225], v[152:153], v[224:225]
	v_pk_mul_f32 v[226:227], v[154:155], v[226:227]
	s_nop 1
	v_permlane16_swap_b32_e32 v220, v224
	v_permlane16_swap_b32_e32 v221, v225
	v_permlane16_swap_b32_e32 v222, v226
	v_permlane16_swap_b32_e32 v223, v227
	v_permlane32_swap_b32_e32 v220, v224
	v_permlane32_swap_b32_e32 v221, v225
	v_permlane32_swap_b32_e32 v222, v226
	v_permlane32_swap_b32_e32 v223, v227
	s_nop 1
	global_store_dwordx4 v[246:247], v[220:223], off offset:0
	global_store_dwordx4 v[246:247], v[224:227], off offset:64
	v_pk_mul_f32 v[228:229], v[84:85], v[184:185] op_sel_hi:[1,0]
	v_pk_mul_f32 v[230:231], v[86:87], v[184:185] op_sel_hi:[1,0]
	v_pk_mul_f32 v[232:233], v[80:81], v[184:185] op_sel_hi:[1,0]
	v_pk_mul_f32 v[234:235], v[82:83], v[184:185] op_sel_hi:[1,0]
	v_pk_mul_f32 v[228:229], v[156:157], v[228:229]
	v_pk_mul_f32 v[230:231], v[158:159], v[230:231]
	v_pk_mul_f32 v[232:233], v[160:161], v[232:233]
	v_pk_mul_f32 v[234:235], v[162:163], v[234:235]
	s_nop 1
	v_permlane16_swap_b32_e32 v228, v232
	v_permlane16_swap_b32_e32 v229, v233
	v_permlane16_swap_b32_e32 v230, v234
	v_permlane16_swap_b32_e32 v231, v235
	v_permlane32_swap_b32_e32 v228, v232
	v_permlane32_swap_b32_e32 v229, v233
	v_permlane32_swap_b32_e32 v230, v234
	v_permlane32_swap_b32_e32 v231, v235
	s_nop 1
	global_store_dwordx4 v[246:247], v[228:231], off offset:512
	global_store_dwordx4 v[246:247], v[232:235], off offset:576
	v_fmamk_f32 v128, v167, 0x3a000000, v177
	v_mul_f32_e32 v129, 0x4f800000, v128
	v_cmp_gt_f32_e32 vcc, s9, v128
	s_nop 1
	v_cndmask_b32_e32 v128, v128, v129, vcc
	v_sqrt_f32_e32 v129, v128
	s_nop 0
	v_add_u32_e32 v130, -1, v129
	v_add_u32_e32 v131, 1, v129
	v_fma_f32 v132, -v130, v129, v128
	v_fma_f32 v133, -v131, v129, v128
	v_cmp_ge_f32_e64 s[2:3], 0, v132
	s_nop 1
	v_cndmask_b32_e64 v129, v129, v130, s[2:3]
	v_cmp_lt_f32_e64 s[2:3], 0, v133
	s_nop 1
	v_cndmask_b32_e64 v129, v129, v131, s[2:3]
	v_mul_f32_e32 v130, 0x37800000, v129
	v_cndmask_b32_e32 v129, v129, v130, vcc
	v_cmp_class_f32_e32 vcc, v128, v178
	s_nop 1
	v_cndmask_b32_e32 v128, v129, v128, vcc
	v_div_scale_f32 v129, s[2:3], v128, v128, 1.0
	v_rcp_f32_e32 v130, v129
	v_div_scale_f32 v131, vcc, 1.0, v128, 1.0
	v_fma_f32 v132, -v129, v130, 1.0
	v_fmac_f32_e32 v130, v132, v130
	v_mul_f32_e32 v132, v131, v130
	v_fma_f32 v133, -v129, v132, v131
	v_fmac_f32_e32 v132, v133, v130
	v_fma_f32 v129, -v129, v132, v131
	v_div_fmas_f32 v129, v129, v130, v132
	v_div_fixup_f32 v184, v129, v128, 1.0
	s_add_u32 s100, s64, 0x60000
	s_addc_u32 s101, s65, 0
	v_lshl_add_u64 v[248:249], s[100:101], 0, v[244:245]
	v_pk_mul_f32 v[188:189], v[76:77], v[184:185] op_sel_hi:[1,0]
	v_pk_mul_f32 v[190:191], v[78:79], v[184:185] op_sel_hi:[1,0]
	v_pk_mul_f32 v[192:193], v[72:73], v[184:185] op_sel_hi:[1,0]
	v_pk_mul_f32 v[194:195], v[74:75], v[184:185] op_sel_hi:[1,0]
	v_pk_mul_f32 v[188:189], v[148:149], v[188:189]
	v_pk_mul_f32 v[190:191], v[150:151], v[190:191]
	v_pk_mul_f32 v[192:193], v[152:153], v[192:193]
	v_pk_mul_f32 v[194:195], v[154:155], v[194:195]
	s_nop 1
	v_permlane16_swap_b32_e32 v188, v192
	v_permlane16_swap_b32_e32 v189, v193
	v_permlane16_swap_b32_e32 v190, v194
	v_permlane16_swap_b32_e32 v191, v195
	v_permlane32_swap_b32_e32 v188, v192
	v_permlane32_swap_b32_e32 v189, v193
	v_permlane32_swap_b32_e32 v190, v194
	v_permlane32_swap_b32_e32 v191, v195
	s_nop 1
	global_store_dwordx4 v[248:249], v[188:191], off offset:0
	global_store_dwordx4 v[248:249], v[192:195], off offset:64
	v_pk_mul_f32 v[196:197], v[68:69], v[184:185] op_sel_hi:[1,0]
	v_pk_mul_f32 v[198:199], v[70:71], v[184:185] op_sel_hi:[1,0]
	v_pk_mul_f32 v[200:201], v[64:65], v[184:185] op_sel_hi:[1,0]
	v_pk_mul_f32 v[202:203], v[66:67], v[184:185] op_sel_hi:[1,0]
	v_pk_mul_f32 v[196:197], v[156:157], v[196:197]
	v_pk_mul_f32 v[198:199], v[158:159], v[198:199]
	v_pk_mul_f32 v[200:201], v[160:161], v[200:201]
	v_pk_mul_f32 v[202:203], v[162:163], v[202:203]
	s_nop 1
	v_permlane16_swap_b32_e32 v196, v200
	v_permlane16_swap_b32_e32 v197, v201
	v_permlane16_swap_b32_e32 v198, v202
	v_permlane16_swap_b32_e32 v199, v203
	v_permlane32_swap_b32_e32 v196, v200
	v_permlane32_swap_b32_e32 v197, v201
	v_permlane32_swap_b32_e32 v198, v202
	v_permlane32_swap_b32_e32 v199, v203
	s_nop 1
	global_store_dwordx4 v[248:249], v[196:199], off offset:512
	global_store_dwordx4 v[248:249], v[200:203], off offset:576
	v_fmamk_f32 v128, v168, 0x3a000000, v177
	v_mul_f32_e32 v129, 0x4f800000, v128
	v_cmp_gt_f32_e32 vcc, s9, v128
	s_nop 1
	v_cndmask_b32_e32 v128, v128, v129, vcc
	v_sqrt_f32_e32 v129, v128
	s_nop 0
	v_add_u32_e32 v130, -1, v129
	v_add_u32_e32 v131, 1, v129
	v_fma_f32 v132, -v130, v129, v128
	v_fma_f32 v133, -v131, v129, v128
	v_cmp_ge_f32_e64 s[2:3], 0, v132
	s_nop 1
	v_cndmask_b32_e64 v129, v129, v130, s[2:3]
	v_cmp_lt_f32_e64 s[2:3], 0, v133
	s_nop 1
	v_cndmask_b32_e64 v129, v129, v131, s[2:3]
	v_mul_f32_e32 v130, 0x37800000, v129
	v_cndmask_b32_e32 v129, v129, v130, vcc
	v_cmp_class_f32_e32 vcc, v128, v178
	s_nop 1
	v_cndmask_b32_e32 v128, v129, v128, vcc
	v_div_scale_f32 v129, s[2:3], v128, v128, 1.0
	v_rcp_f32_e32 v130, v129
	v_div_scale_f32 v131, vcc, 1.0, v128, 1.0
	v_fma_f32 v132, -v129, v130, 1.0
	v_fmac_f32_e32 v130, v132, v130
	v_mul_f32_e32 v132, v131, v130
	v_fma_f32 v133, -v129, v132, v131
	v_fmac_f32_e32 v132, v133, v130
	v_fma_f32 v129, -v129, v132, v131
	v_div_fmas_f32 v129, v129, v130, v132
	v_div_fixup_f32 v184, v129, v128, 1.0
	s_add_u32 s100, s64, 0x100000
	s_addc_u32 s101, s65, 0
	v_lshl_add_u64 v[246:247], s[100:101], 0, v[244:245]
	v_pk_mul_f32 v[204:205], v[60:61], v[184:185] op_sel_hi:[1,0]
	v_pk_mul_f32 v[206:207], v[62:63], v[184:185] op_sel_hi:[1,0]
	v_pk_mul_f32 v[208:209], v[56:57], v[184:185] op_sel_hi:[1,0]
	v_pk_mul_f32 v[210:211], v[58:59], v[184:185] op_sel_hi:[1,0]
	v_pk_mul_f32 v[204:205], v[148:149], v[204:205]
	v_pk_mul_f32 v[206:207], v[150:151], v[206:207]
	v_pk_mul_f32 v[208:209], v[152:153], v[208:209]
	v_pk_mul_f32 v[210:211], v[154:155], v[210:211]
	s_nop 1
	v_permlane16_swap_b32_e32 v204, v208
	v_permlane16_swap_b32_e32 v205, v209
	v_permlane16_swap_b32_e32 v206, v210
	v_permlane16_swap_b32_e32 v207, v211
	v_permlane32_swap_b32_e32 v204, v208
	v_permlane32_swap_b32_e32 v205, v209
	v_permlane32_swap_b32_e32 v206, v210
	v_permlane32_swap_b32_e32 v207, v211
	s_nop 1
	global_store_dwordx4 v[246:247], v[204:207], off offset:0
	global_store_dwordx4 v[246:247], v[208:211], off offset:64
	v_pk_mul_f32 v[212:213], v[52:53], v[184:185] op_sel_hi:[1,0]
	v_pk_mul_f32 v[214:215], v[54:55], v[184:185] op_sel_hi:[1,0]
	v_pk_mul_f32 v[216:217], v[48:49], v[184:185] op_sel_hi:[1,0]
	v_pk_mul_f32 v[218:219], v[50:51], v[184:185] op_sel_hi:[1,0]
	v_pk_mul_f32 v[212:213], v[156:157], v[212:213]
	v_pk_mul_f32 v[214:215], v[158:159], v[214:215]
	v_pk_mul_f32 v[216:217], v[160:161], v[216:217]
	v_pk_mul_f32 v[218:219], v[162:163], v[218:219]
	s_nop 1
	v_permlane16_swap_b32_e32 v212, v216
	v_permlane16_swap_b32_e32 v213, v217
	v_permlane16_swap_b32_e32 v214, v218
	v_permlane16_swap_b32_e32 v215, v219
	v_permlane32_swap_b32_e32 v212, v216
	v_permlane32_swap_b32_e32 v213, v217
	v_permlane32_swap_b32_e32 v214, v218
	v_permlane32_swap_b32_e32 v215, v219
	s_nop 1
	global_store_dwordx4 v[246:247], v[212:215], off offset:512
	global_store_dwordx4 v[246:247], v[216:219], off offset:576
	v_fmamk_f32 v128, v169, 0x3a000000, v177
	v_mul_f32_e32 v129, 0x4f800000, v128
	v_cmp_gt_f32_e32 vcc, s9, v128
	s_nop 1
	v_cndmask_b32_e32 v128, v128, v129, vcc
	v_sqrt_f32_e32 v129, v128
	s_nop 0
	v_add_u32_e32 v130, -1, v129
	v_add_u32_e32 v131, 1, v129
	v_fma_f32 v132, -v130, v129, v128
	v_fma_f32 v133, -v131, v129, v128
	v_cmp_ge_f32_e64 s[2:3], 0, v132
	s_nop 1
	v_cndmask_b32_e64 v129, v129, v130, s[2:3]
	v_cmp_lt_f32_e64 s[2:3], 0, v133
	s_nop 1
	v_cndmask_b32_e64 v129, v129, v131, s[2:3]
	v_mul_f32_e32 v130, 0x37800000, v129
	v_cndmask_b32_e32 v129, v129, v130, vcc
	v_cmp_class_f32_e32 vcc, v128, v178
	s_nop 1
	v_cndmask_b32_e32 v128, v129, v128, vcc
	v_div_scale_f32 v129, s[2:3], v128, v128, 1.0
	v_rcp_f32_e32 v130, v129
	v_div_scale_f32 v131, vcc, 1.0, v128, 1.0
	v_fma_f32 v132, -v129, v130, 1.0
	v_fmac_f32_e32 v130, v132, v130
	v_mul_f32_e32 v132, v131, v130
	v_fma_f32 v133, -v129, v132, v131
	v_fmac_f32_e32 v132, v133, v130
	v_fma_f32 v129, -v129, v132, v131
	v_div_fmas_f32 v129, v129, v130, v132
	v_div_fixup_f32 v184, v129, v128, 1.0
	s_add_u32 s100, s64, 0x120000
	s_addc_u32 s101, s65, 0
	v_lshl_add_u64 v[248:249], s[100:101], 0, v[244:245]
	v_pk_mul_f32 v[220:221], v[44:45], v[184:185] op_sel_hi:[1,0]
	v_pk_mul_f32 v[222:223], v[46:47], v[184:185] op_sel_hi:[1,0]
	v_pk_mul_f32 v[224:225], v[40:41], v[184:185] op_sel_hi:[1,0]
	v_pk_mul_f32 v[226:227], v[42:43], v[184:185] op_sel_hi:[1,0]
	v_pk_mul_f32 v[220:221], v[148:149], v[220:221]
	v_pk_mul_f32 v[222:223], v[150:151], v[222:223]
	v_pk_mul_f32 v[224:225], v[152:153], v[224:225]
	v_pk_mul_f32 v[226:227], v[154:155], v[226:227]
	s_nop 1
	v_permlane16_swap_b32_e32 v220, v224
	v_permlane16_swap_b32_e32 v221, v225
	v_permlane16_swap_b32_e32 v222, v226
	v_permlane16_swap_b32_e32 v223, v227
	v_permlane32_swap_b32_e32 v220, v224
	v_permlane32_swap_b32_e32 v221, v225
	v_permlane32_swap_b32_e32 v222, v226
	v_permlane32_swap_b32_e32 v223, v227
	s_nop 1
	global_store_dwordx4 v[248:249], v[220:223], off offset:0
	global_store_dwordx4 v[248:249], v[224:227], off offset:64
	v_pk_mul_f32 v[228:229], v[36:37], v[184:185] op_sel_hi:[1,0]
	v_pk_mul_f32 v[230:231], v[38:39], v[184:185] op_sel_hi:[1,0]
	v_pk_mul_f32 v[232:233], v[32:33], v[184:185] op_sel_hi:[1,0]
	v_pk_mul_f32 v[234:235], v[34:35], v[184:185] op_sel_hi:[1,0]
	v_pk_mul_f32 v[228:229], v[156:157], v[228:229]
	v_pk_mul_f32 v[230:231], v[158:159], v[230:231]
	v_pk_mul_f32 v[232:233], v[160:161], v[232:233]
	v_pk_mul_f32 v[234:235], v[162:163], v[234:235]
	s_nop 1
	v_permlane16_swap_b32_e32 v228, v232
	v_permlane16_swap_b32_e32 v229, v233
	v_permlane16_swap_b32_e32 v230, v234
	v_permlane16_swap_b32_e32 v231, v235
	v_permlane32_swap_b32_e32 v228, v232
	v_permlane32_swap_b32_e32 v229, v233
	v_permlane32_swap_b32_e32 v230, v234
	v_permlane32_swap_b32_e32 v231, v235
	s_nop 1
	global_store_dwordx4 v[248:249], v[228:231], off offset:512
	global_store_dwordx4 v[248:249], v[232:235], off offset:576
	v_fmamk_f32 v128, v170, 0x3a000000, v177
	v_mul_f32_e32 v129, 0x4f800000, v128
	v_cmp_gt_f32_e32 vcc, s9, v128
	s_nop 1
	v_cndmask_b32_e32 v128, v128, v129, vcc
	v_sqrt_f32_e32 v129, v128
	s_nop 0
	v_add_u32_e32 v130, -1, v129
	v_add_u32_e32 v131, 1, v129
	v_fma_f32 v132, -v130, v129, v128
	v_fma_f32 v133, -v131, v129, v128
	v_cmp_ge_f32_e64 s[2:3], 0, v132
	s_nop 1
	v_cndmask_b32_e64 v129, v129, v130, s[2:3]
	v_cmp_lt_f32_e64 s[2:3], 0, v133
	s_nop 1
	v_cndmask_b32_e64 v129, v129, v131, s[2:3]
	v_mul_f32_e32 v130, 0x37800000, v129
	v_cndmask_b32_e32 v129, v129, v130, vcc
	v_cmp_class_f32_e32 vcc, v128, v178
	s_nop 1
	v_cndmask_b32_e32 v128, v129, v128, vcc
	v_div_scale_f32 v129, s[2:3], v128, v128, 1.0
	v_rcp_f32_e32 v130, v129
	v_div_scale_f32 v131, vcc, 1.0, v128, 1.0
	v_fma_f32 v132, -v129, v130, 1.0
	v_fmac_f32_e32 v130, v132, v130
	v_mul_f32_e32 v132, v131, v130
	v_fma_f32 v133, -v129, v132, v131
	v_fmac_f32_e32 v132, v133, v130
	v_fma_f32 v129, -v129, v132, v131
	v_div_fmas_f32 v129, v129, v130, v132
	v_div_fixup_f32 v184, v129, v128, 1.0
	s_add_u32 s100, s64, 0x140000
	s_addc_u32 s101, s65, 0
	v_lshl_add_u64 v[246:247], s[100:101], 0, v[244:245]
	v_pk_mul_f32 v[188:189], v[28:29], v[184:185] op_sel_hi:[1,0]
	v_pk_mul_f32 v[190:191], v[30:31], v[184:185] op_sel_hi:[1,0]
	v_pk_mul_f32 v[192:193], v[24:25], v[184:185] op_sel_hi:[1,0]
	v_pk_mul_f32 v[194:195], v[26:27], v[184:185] op_sel_hi:[1,0]
	v_pk_mul_f32 v[188:189], v[148:149], v[188:189]
	v_pk_mul_f32 v[190:191], v[150:151], v[190:191]
	v_pk_mul_f32 v[192:193], v[152:153], v[192:193]
	v_pk_mul_f32 v[194:195], v[154:155], v[194:195]
	s_nop 1
	v_permlane16_swap_b32_e32 v188, v192
	v_permlane16_swap_b32_e32 v189, v193
	v_permlane16_swap_b32_e32 v190, v194
	v_permlane16_swap_b32_e32 v191, v195
	v_permlane32_swap_b32_e32 v188, v192
	v_permlane32_swap_b32_e32 v189, v193
	v_permlane32_swap_b32_e32 v190, v194
	v_permlane32_swap_b32_e32 v191, v195
	s_nop 1
	global_store_dwordx4 v[246:247], v[188:191], off offset:0
	global_store_dwordx4 v[246:247], v[192:195], off offset:64
	v_pk_mul_f32 v[196:197], v[20:21], v[184:185] op_sel_hi:[1,0]
	v_pk_mul_f32 v[198:199], v[22:23], v[184:185] op_sel_hi:[1,0]
	v_pk_mul_f32 v[200:201], v[16:17], v[184:185] op_sel_hi:[1,0]
	v_pk_mul_f32 v[202:203], v[18:19], v[184:185] op_sel_hi:[1,0]
	v_pk_mul_f32 v[196:197], v[156:157], v[196:197]
	v_pk_mul_f32 v[198:199], v[158:159], v[198:199]
	v_pk_mul_f32 v[200:201], v[160:161], v[200:201]
	v_pk_mul_f32 v[202:203], v[162:163], v[202:203]
	s_nop 1
	v_permlane16_swap_b32_e32 v196, v200
	v_permlane16_swap_b32_e32 v197, v201
	v_permlane16_swap_b32_e32 v198, v202
	v_permlane16_swap_b32_e32 v199, v203
	v_permlane32_swap_b32_e32 v196, v200
	v_permlane32_swap_b32_e32 v197, v201
	v_permlane32_swap_b32_e32 v198, v202
	v_permlane32_swap_b32_e32 v199, v203
	s_nop 1
	global_store_dwordx4 v[246:247], v[196:199], off offset:512
	global_store_dwordx4 v[246:247], v[200:203], off offset:576
	v_fmamk_f32 v128, v171, 0x3a000000, v177
	v_mul_f32_e32 v129, 0x4f800000, v128
	v_cmp_gt_f32_e32 vcc, s9, v128
	s_nop 1
	v_cndmask_b32_e32 v128, v128, v129, vcc
	v_sqrt_f32_e32 v129, v128
	s_nop 0
	v_add_u32_e32 v130, -1, v129
	v_add_u32_e32 v131, 1, v129
	v_fma_f32 v132, -v130, v129, v128
	v_fma_f32 v133, -v131, v129, v128
	v_cmp_ge_f32_e64 s[2:3], 0, v132
	s_nop 1
	v_cndmask_b32_e64 v129, v129, v130, s[2:3]
	v_cmp_lt_f32_e64 s[2:3], 0, v133
	s_nop 1
	v_cndmask_b32_e64 v129, v129, v131, s[2:3]
	v_mul_f32_e32 v130, 0x37800000, v129
	v_cndmask_b32_e32 v129, v129, v130, vcc
	v_cmp_class_f32_e32 vcc, v128, v178
	s_nop 1
	v_cndmask_b32_e32 v128, v129, v128, vcc
	v_div_scale_f32 v129, s[2:3], v128, v128, 1.0
	v_rcp_f32_e32 v130, v129
	v_div_scale_f32 v131, vcc, 1.0, v128, 1.0
	v_fma_f32 v132, -v129, v130, 1.0
	v_fmac_f32_e32 v130, v132, v130
	v_mul_f32_e32 v132, v131, v130
	v_fma_f32 v133, -v129, v132, v131
	v_fmac_f32_e32 v132, v133, v130
	v_fma_f32 v129, -v129, v132, v131
	v_div_fmas_f32 v129, v129, v130, v132
	v_div_fixup_f32 v184, v129, v128, 1.0
	s_add_u32 s100, s64, 0x160000
	s_addc_u32 s101, s65, 0
	v_lshl_add_u64 v[248:249], s[100:101], 0, v[244:245]
	v_pk_mul_f32 v[204:205], v[12:13], v[184:185] op_sel_hi:[1,0]
	v_pk_mul_f32 v[206:207], v[14:15], v[184:185] op_sel_hi:[1,0]
	v_pk_mul_f32 v[208:209], v[8:9], v[184:185] op_sel_hi:[1,0]
	v_pk_mul_f32 v[210:211], v[10:11], v[184:185] op_sel_hi:[1,0]
	v_pk_mul_f32 v[204:205], v[148:149], v[204:205]
	v_pk_mul_f32 v[206:207], v[150:151], v[206:207]
	v_pk_mul_f32 v[208:209], v[152:153], v[208:209]
	v_pk_mul_f32 v[210:211], v[154:155], v[210:211]
	s_nop 1
	v_permlane16_swap_b32_e32 v204, v208
	v_permlane16_swap_b32_e32 v205, v209
	v_permlane16_swap_b32_e32 v206, v210
	v_permlane16_swap_b32_e32 v207, v211
	v_permlane32_swap_b32_e32 v204, v208
	v_permlane32_swap_b32_e32 v205, v209
	v_permlane32_swap_b32_e32 v206, v210
	v_permlane32_swap_b32_e32 v207, v211
	s_nop 1
	global_store_dwordx4 v[248:249], v[204:207], off offset:0
	global_store_dwordx4 v[248:249], v[208:211], off offset:64
	v_pk_mul_f32 v[212:213], v[4:5], v[184:185] op_sel_hi:[1,0]
	v_pk_mul_f32 v[214:215], v[6:7], v[184:185] op_sel_hi:[1,0]
	v_pk_mul_f32 v[216:217], v[0:1], v[184:185] op_sel_hi:[1,0]
	v_pk_mul_f32 v[218:219], v[2:3], v[184:185] op_sel_hi:[1,0]
	v_pk_mul_f32 v[212:213], v[156:157], v[212:213]
	v_pk_mul_f32 v[214:215], v[158:159], v[214:215]
	v_pk_mul_f32 v[216:217], v[160:161], v[216:217]
	v_pk_mul_f32 v[218:219], v[162:163], v[218:219]
	s_nop 1
	v_permlane16_swap_b32_e32 v212, v216
	v_permlane16_swap_b32_e32 v213, v217
	v_permlane16_swap_b32_e32 v214, v218
	v_permlane16_swap_b32_e32 v215, v219
	v_permlane32_swap_b32_e32 v212, v216
	v_permlane32_swap_b32_e32 v213, v217
	v_permlane32_swap_b32_e32 v214, v218
	v_permlane32_swap_b32_e32 v215, v219
	s_nop 1
	global_store_dwordx4 v[248:249], v[212:215], off offset:512
	global_store_dwordx4 v[248:249], v[216:219], off offset:576
	s_andn2_b64 vcc, exec, s[22:23]
	s_mov_b64 s[2:3], -1
	s_cbranch_vccnz .LBB0_672
	s_and_b64 vcc, exec, s[0:1]
	s_cbranch_vccnz .LBB0_671
	s_barrier
	s_branch .LBB0_671
